# attention main loop: K/V tile LDS-DMA addresses formed on the SALU (scalar base + 32-bit lane offset) instead of v_mad_u64_u32 + v_lshl_add_u64 per load
# speedup vs baseline: 1.0033x; 1.0017x over previous
.LBB0_1314:
	v_lshlrev_b32_e32 v0, 1, v216
	v_and_b32_e32 v223, 32, v0
	v_lshrrev_b32_e32 v0, 2, v216
	v_and_or_b32 v0, v0, 3, v221
	v_lshlrev_b32_e32 v222, 6, v0
	v_add_u32_e32 v0, 0, v223
	v_add3_u32 v240, v0, v220, v222
	v_max3_f32 v0, v2, v3, v18
	v_max3_f32 v34, v4, v5, v19
	s_lshl_b32 s71, s24, 8
	v_max3_f32 v0, v0, v20, v21
	v_max3_f32 v34, v34, v8, v9
	s_and_b32 s17, s17, 0x3fffffc0
	v_max3_f32 v0, v0, v6, v7
	v_max3_f32 v34, v34, v24, v25
	s_add_i32 s76, s71, 0x100
	v_max3_f32 v0, v0, v22, v23
	v_max3_f32 v34, v34, v12, v13
	s_lshl_b32 s17, s17, 2
	v_max3_f32 v0, v0, v10, v11
	v_max3_f32 v34, v34, v28, v29
	s_add_i32 s17, s17, 0
	v_max3_f32 v0, v0, v26, v27
	v_max3_f32 v34, v34, v16, v17
	s_lshr_b32 s77, s76, 6
	v_max3_f32 v0, v0, v14, v15
	v_max3_f32 v34, v34, v32, v33
	s_mov_b64 s[22:23], 0x30000
	v_max3_f32 v0, v0, v30, v31
	s_cmp_lg_u32 0, -1
	v_max_f32_e32 v0, v0, v34
	s_mov_b32 s50, 1
	v_mov_b32_e32 v34, v0
	s_nop 1
	v_permlane32_swap_b32_e32 v0, v34
	v_max_f32_e32 v0, v0, v34
	s_mov_b32 s25, 0
	v_add_f32_e32 v229, v1, v0
	v_sub_f32_e32 v2, v2, v0
	v_sub_f32_e32 v3, v3, v0
	v_sub_f32_e32 v18, v18, v0
	v_sub_f32_e32 v19, v19, v0
	v_sub_f32_e32 v4, v4, v0
	s_nop 0
	v_xor_b32_e32 v48, 0x80000000, v229
	v_mov_b32_e32 v49, v48
	v_mov_b32_e32 v50, v48
	v_mov_b32_e32 v51, v48
	v_mov_b32_e32 v52, v48
	v_mov_b32_e32 v53, v48
	v_mov_b32_e32 v54, v48
	v_mov_b32_e32 v55, v48
	v_mov_b32_e32 v56, v48
	v_mov_b32_e32 v57, v48
	v_mov_b32_e32 v58, v48
	v_mov_b32_e32 v59, v48
	v_mov_b32_e32 v60, v48
	v_mov_b32_e32 v61, v48
	v_mov_b32_e32 v62, v48
	v_mov_b32_e32 v63, v48
	s_waitcnt vmcnt(0) lgkmcnt(0)
	s_barrier
	v_exp_f32_e32 v80, v2
	v_exp_f32_e32 v81, v3
	v_lshl_add_u64 v[2:3], v[212:213], 0, s[22:23]
	s_mov_b32 s22, m0
	s_mov_b32 m0, s74
	s_nop 0
	global_load_lds_dwordx4 v[2:3], off
	s_mov_b32 m0, s22
	s_cselect_b32 s22, 0, 0
	s_add_i32 s16, s22, s16
	v_lshl_add_u64 v[2:3], v[214:215], 0, s[30:31]
	s_add_i32 s16, s16, 0x8000
	s_mov_b32 s22, m0
	s_mov_b32 m0, s16
	s_nop 0
	global_load_lds_dwordx4 v[2:3], off
	s_mov_b32 m0, s22
	ds_read_b128 v[188:191], v228 offset:8192
	ds_read_b128 v[184:187], v228 offset:8704
	ds_read_b128 v[180:183], v228 offset:10240
	ds_read_b128 v[176:179], v228 offset:10752
	ds_read_b128 v[172:175], v228 offset:12288
	ds_read_b128 v[168:171], v228 offset:12800
	ds_read_b128 v[164:167], v228 offset:14336
	ds_read_b128 v[160:163], v228 offset:14848
	v_sub_f32_e32 v20, v20, v0
	v_sub_f32_e32 v5, v5, v0
	v_sub_f32_e32 v21, v21, v0
	v_sub_f32_e32 v6, v6, v0
	v_sub_f32_e32 v22, v22, v0
	v_sub_f32_e32 v7, v7, v0
	v_sub_f32_e32 v23, v23, v0
	v_sub_f32_e32 v8, v8, v0
	v_sub_f32_e32 v24, v24, v0
	v_sub_f32_e32 v9, v9, v0
	v_sub_f32_e32 v25, v25, v0
	v_sub_f32_e32 v10, v10, v0
	v_sub_f32_e32 v26, v26, v0
	v_sub_f32_e32 v11, v11, v0
	v_sub_f32_e32 v27, v27, v0
	v_sub_f32_e32 v12, v12, v0
	v_sub_f32_e32 v28, v28, v0
	v_sub_f32_e32 v13, v13, v0
	v_sub_f32_e32 v29, v29, v0
	v_sub_f32_e32 v14, v14, v0
	v_sub_f32_e32 v30, v30, v0
	v_sub_f32_e32 v15, v15, v0
	v_sub_f32_e32 v31, v31, v0
	v_sub_f32_e32 v16, v16, v0
	v_sub_f32_e32 v32, v32, v0
	v_sub_f32_e32 v17, v17, v0
	v_sub_f32_e32 v0, v33, v0
	v_exp_f32_e32 v82, v4
	v_exp_f32_e32 v83, v5
	v_exp_f32_e32 v84, v6
	v_exp_f32_e32 v85, v7
	v_exp_f32_e32 v86, v8
	v_exp_f32_e32 v87, v9
	v_exp_f32_e32 v88, v10
	v_exp_f32_e32 v89, v11
	v_exp_f32_e32 v90, v12
	v_exp_f32_e32 v91, v13
	v_exp_f32_e32 v92, v14
	v_exp_f32_e32 v93, v15
	v_exp_f32_e32 v94, v16
	v_exp_f32_e32 v95, v17
	v_exp_f32_e32 v64, v18
	v_exp_f32_e32 v65, v19
	v_exp_f32_e32 v66, v20
	v_exp_f32_e32 v67, v21
	v_exp_f32_e32 v68, v22
	v_exp_f32_e32 v69, v23
	v_exp_f32_e32 v70, v24
	v_exp_f32_e32 v71, v25
	v_exp_f32_e32 v72, v26
	v_exp_f32_e32 v73, v27
	v_exp_f32_e32 v74, v28
	v_exp_f32_e32 v75, v29
	v_exp_f32_e32 v76, v30
	v_exp_f32_e32 v77, v31
	v_exp_f32_e32 v78, v32
	v_exp_f32_e32 v79, v0
	s_waitcnt vmcnt(2) lgkmcnt(0)
	s_barrier
	s_andn2_b64 vcc, exec, s[2:3]
	v_cmp_gt_u32_e64 s[2:3], 32, v217
	v_lshl_add_u32 v226, v218, 2, s17
	v_lshl_add_u32 v224, v221, 2, s17
	s_cbranch_vccnz .LBB0_1330
	v_mov_b32_e32 v14, v1
	v_mov_b32_e32 v15, v1
	v_readlane_b32 s16, v255, 9
	v_mov_b32_e32 v0, v1
	v_mov_b32_e32 v2, v1
	v_mov_b32_e32 v3, v1
	v_mov_b32_e32 v4, v1
	v_mov_b32_e32 v5, v1
	v_mov_b32_e32 v6, v1
	v_mov_b32_e32 v7, v1
	v_mov_b32_e32 v8, v1
	v_mov_b32_e32 v9, v1
	v_mov_b32_e32 v10, v1
	v_mov_b32_e32 v11, v1
	v_mov_b32_e32 v12, v1
	v_mov_b32_e32 v13, v1
	v_mov_b64_e32 v[46:47], v[14:15]
	v_mov_b64_e32 v[30:31], v[14:15]
	v_lshl_add_u32 v200, v219, 4, s16
	v_readfirstlane_b32 s98, v212
	v_readfirstlane_b32 s99, v213
	v_subrev_u32_e32 v236, s98, v212
	v_subrev_u32_e32 v237, s98, v214
	s_mov_b32 s16, 0
	s_movk_i32 s25, 0x4000
	s_movk_i32 s50, 0x2000
	v_mov_b32_e32 v241, 0
	s_mov_b32 s46, 6
	s_mov_b32 s47, 0x20000
	v_mov_b64_e32 v[44:45], v[12:13]
	v_mov_b64_e32 v[42:43], v[10:11]
	v_mov_b64_e32 v[40:41], v[8:9]
	v_mov_b64_e32 v[38:39], v[6:7]
	v_mov_b64_e32 v[36:37], v[4:5]
	v_mov_b64_e32 v[34:35], v[2:3]
	v_mov_b64_e32 v[32:33], v[0:1]
	v_mov_b64_e32 v[28:29], v[12:13]
	v_mov_b64_e32 v[26:27], v[10:11]
	v_mov_b64_e32 v[24:25], v[8:9]
	v_mov_b64_e32 v[22:23], v[6:7]
	v_mov_b64_e32 v[20:21], v[4:5]
	v_mov_b64_e32 v[18:19], v[2:3]
	v_mov_b64_e32 v[16:17], v[0:1]
	.p2align	6
.LBB0_1316:
	v_add_u32_e32 v0, s16, v240
	ds_read_b64_tr_b16 v[192:193], v0 offset:24576
	ds_read_b64_tr_b16 v[194:195], v0 offset:25088
	v_add_f32_e32 v2, v80, v81
	v_add_f32_e32 v2, v82, v2
	v_add_f32_e32 v2, v83, v2
	v_add_f32_e32 v2, v84, v2
	v_add_f32_e32 v2, v85, v2
	v_cvt_pk_bf16_f32 v156, v80, v81
	v_cvt_pk_bf16_f32 v157, v82, v83
	s_waitcnt lgkmcnt(9)
	v_mfma_f32_32x32x16_bf16 v[96:111], v[188:191], v[140:143], v[48:63]
	ds_read_b64_tr_b16 v[188:189], v0 offset:28672
	ds_read_b64_tr_b16 v[190:191], v0 offset:29184
	v_add_f32_e32 v2, v86, v2
	v_add_f32_e32 v2, v87, v2
	v_add_f32_e32 v2, v88, v2
	v_add_f32_e32 v2, v89, v2
	v_cvt_pk_bf16_f32 v158, v84, v85
	v_cvt_pk_bf16_f32 v159, v86, v87
	s_waitcnt lgkmcnt(10)
	v_mfma_f32_32x32x16_bf16 v[112:127], v[184:187], v[140:143], v[48:63]
	ds_read_b64_tr_b16 v[10:11], v0 offset:25600
	ds_read_b64_tr_b16 v[12:13], v0 offset:26112
	v_add_f32_e32 v2, v90, v2
	v_add_f32_e32 v2, v91, v2
	v_add_f32_e32 v2, v92, v2
	v_add_f32_e32 v2, v93, v2
	v_cvt_pk_bf16_f32 v152, v88, v89
	v_cvt_pk_bf16_f32 v153, v90, v91
	s_waitcnt lgkmcnt(11)
	v_mfma_f32_32x32x16_bf16 v[96:111], v[180:183], v[136:139], v[96:111]
	ds_read_b64_tr_b16 v[180:181], v0 offset:29696
	ds_read_b64_tr_b16 v[182:183], v0 offset:30208
	v_add_f32_e32 v2, v94, v2
	v_add_f32_e32 v2, v95, v2
	v_add_f32_e32 v2, v64, v2
	v_add_f32_e32 v2, v65, v2
	v_cvt_pk_bf16_f32 v154, v92, v93
	v_cvt_pk_bf16_f32 v155, v94, v95
	s_waitcnt lgkmcnt(12)
	v_mfma_f32_32x32x16_bf16 v[112:127], v[176:179], v[136:139], v[112:127]
	ds_read_b64_tr_b16 v[176:177], v0 offset:26624
	ds_read_b64_tr_b16 v[178:179], v0 offset:27136
	v_add_f32_e32 v2, v66, v2
	v_add_f32_e32 v2, v67, v2
	v_add_f32_e32 v2, v68, v2
	v_add_f32_e32 v6, v69, v2
	v_cvt_pk_bf16_f32 v148, v64, v65
	v_cvt_pk_bf16_f32 v149, v66, v67
	ds_read_b128 v[64:67], v200
	s_waitcnt lgkmcnt(13)
	v_mfma_f32_32x32x16_bf16 v[96:111], v[172:175], v[132:135], v[96:111]
	ds_read_b64_tr_b16 v[2:3], v0 offset:30720
	ds_read_b64_tr_b16 v[4:5], v0 offset:31232
	v_add_f32_e32 v6, v70, v6
	v_add_f32_e32 v6, v71, v6
	v_add_f32_e32 v6, v72, v6
	v_add_f32_e32 v14, v73, v6
	v_cvt_pk_bf16_f32 v150, v68, v69
	v_cvt_pk_bf16_f32 v151, v70, v71
	ds_read_b128 v[68:71], v200 offset:32
	s_waitcnt lgkmcnt(14)
	v_mfma_f32_32x32x16_bf16 v[112:127], v[168:171], v[132:135], v[112:127]
	ds_read_b64_tr_b16 v[6:7], v0 offset:27648
	ds_read_b64_tr_b16 v[8:9], v0 offset:28160
	v_add_f32_e32 v14, v74, v14
	v_add_f32_e32 v14, v75, v14
	v_add_f32_e32 v14, v76, v14
	v_add_f32_e32 v14, v77, v14
	v_cvt_pk_bf16_f32 v144, v72, v73
	v_cvt_pk_bf16_f32 v145, v74, v75
	ds_read_b128 v[72:75], v200 offset:128
	s_waitcnt lgkmcnt(14)
	v_mfma_f32_32x32x16_bf16 v[96:111], v[164:167], v[128:131], v[96:111]
	ds_read_b64_tr_b16 v[164:165], v0 offset:31744
	ds_read_b64_tr_b16 v[166:167], v0 offset:32256
	v_add_f32_e32 v0, v78, v14
	v_add_f32_e32 v0, v79, v0
	v_add_f32_e32 v0, 0, v0
	v_cvt_pk_bf16_f32 v146, v76, v77
	v_cvt_pk_bf16_f32 v147, v78, v79
	v_mfma_f32_32x32x16_bf16 v[112:127], v[160:163], v[128:131], v[112:127]
	s_add_i32 s16, s46, -2
	s_lshr_b32 s16, s16, 2
	s_and_b32 s22, s47, 0x18000
	s_mul_i32 s100, s16, 0x180000
	s_lshl_b32 s26, s22, 1
	s_add_u32 s100, s100, s26
	s_add_u32 s100, s100, s98
	s_addc_u32 s101, s99, 0
	s_add_i32 s16, s50, s74
	s_mov_b32 s17, m0
	s_mov_b32 m0, s16
	s_nop 0
	global_load_lds_dwordx4 v236, s[100:101]
	s_mov_b32 m0, s17
	s_add_i32 s16, s46, -4
	s_add_i32 s17, s47, 0xffff0000
	s_lshr_b32 s16, s16, 2
	s_and_b32 s22, s17, 0x18000
	s_mul_i32 s100, s16, 0x180000
	s_lshl_b32 s26, s22, 1
	s_add_u32 s100, s100, s26
	s_add_u32 s100, s100, s98
	s_addc_u32 s101, s99, 0
	s_add_i32 s16, s25, s75
	s_mov_b32 s17, m0
	s_mov_b32 m0, s16
	s_nop 0
	global_load_lds_dwordx4 v237, s[100:101]
	s_mov_b32 m0, s17
	v_add_f32_e32 v0, v241, v0
	s_waitcnt lgkmcnt(2)
	v_add_f32_e32 v82, v98, v66
	v_add_f32_e32 v83, v99, v67
	s_waitcnt lgkmcnt(1)
	v_add_f32_e32 v84, v100, v68
	v_add_f32_e32 v85, v101, v69
	s_waitcnt lgkmcnt(0)
	v_add_f32_e32 v14, v112, v72
	v_add_f32_e32 v15, v113, v73
	v_add_f32_e32 v66, v114, v74
	v_add_f32_e32 v67, v115, v75
	ds_read_b128 v[72:75], v200 offset:160
	v_add_f32_e32 v86, v102, v70
	v_add_f32_e32 v87, v103, v71
	v_add_f32_e32 v64, v96, v64
	v_add_f32_e32 v65, v97, v65
	v_max3_f32 v81, v82, v83, v15
	v_max_f32_e32 v80, v64, v65
	s_waitcnt lgkmcnt(0)
	v_add_f32_e32 v68, v116, v72
	v_add_f32_e32 v69, v117, v73
	v_add_f32_e32 v70, v118, v74
	v_add_f32_e32 v71, v119, v75
	ds_read_b128 v[72:75], v200 offset:64
	ds_read_b128 v[76:79], v200 offset:192
	v_max3_f32 v80, v80, v14, v66
	v_max3_f32 v80, v80, v67, v84
	v_max3_f32 v81, v81, v86, v87
	s_waitcnt lgkmcnt(1)
	v_add_f32_e32 v88, v104, v72
	v_add_f32_e32 v89, v105, v73
	s_waitcnt lgkmcnt(0)
	v_add_f32_e32 v72, v120, v76
	v_add_f32_e32 v73, v121, v77
	v_add_f32_e32 v90, v106, v74
	v_add_f32_e32 v91, v107, v75
	v_add_f32_e32 v74, v122, v78
	v_add_f32_e32 v75, v123, v79
	ds_read_b128 v[76:79], v200 offset:96
	ds_read_b128 v[94:97], v200 offset:224
	v_max3_f32 v80, v80, v85, v68
	v_max3_f32 v81, v81, v70, v71
	v_max3_f32 v80, v80, v69, v88
	v_max3_f32 v81, v81, v90, v91
	s_waitcnt lgkmcnt(1)
	v_add_f32_e32 v92, v108, v76
	v_add_f32_e32 v93, v109, v77
	s_waitcnt lgkmcnt(0)
	v_add_f32_e32 v76, v124, v94
	v_add_f32_e32 v77, v125, v95
	v_add_f32_e32 v94, v110, v78
	v_add_f32_e32 v95, v111, v79
	v_max3_f32 v80, v80, v89, v72
	v_max3_f32 v81, v81, v74, v75
	v_add_f32_e32 v78, v126, v96
	v_add_f32_e32 v79, v127, v97
	v_max3_f32 v80, v80, v73, v92
	v_max3_f32 v81, v81, v94, v95
	v_max3_f32 v80, v80, v93, v76
	v_max3_f32 v81, v81, v78, v79
	v_max3_f32 v80, v80, v77, v81
	v_mov_b32_e32 v81, v80
	s_nop 1
	v_permlane32_swap_b32_e32 v80, v81
	v_max_f32_e32 v81, v81, v81
	v_max_f32_e32 v80, v80, v80
	v_max_f32_e32 v80, v80, v81
	v_cmp_lt_f32_e32 vcc, s36, v80
	s_cmp_lg_u64 vcc, 0
	s_cselect_b64 s[16:17], -1, 0
	s_cbranch_vccnz .LBB0_1324

.LBB0_1319:
	s_add_i32 s16, s25, 0x2000
	s_cmpk_lg_i32 s25, 0x4000
	s_cselect_b32 s78, s16, 0
	v_add_u32_e32 v14, s50, v240
	ds_read_b64_tr_b16 v[168:169], v14 offset:24576
	ds_read_b64_tr_b16 v[170:171], v14 offset:25088
	v_add_f32_e32 v2, v80, v81
	v_add_f32_e32 v2, v82, v2
	v_add_f32_e32 v2, v83, v2
	v_add_f32_e32 v2, v84, v2
	v_add_f32_e32 v2, v85, v2
	v_cvt_pk_bf16_f32 v156, v80, v81
	v_cvt_pk_bf16_f32 v157, v82, v83
	s_waitcnt lgkmcnt(9)
	v_mfma_f32_32x32x16_bf16 v[96:111], v[112:115], v[140:143], v[48:63]
	ds_read_b64_tr_b16 v[164:165], v14 offset:28672
	ds_read_b64_tr_b16 v[166:167], v14 offset:29184
	v_add_f32_e32 v2, v86, v2
	v_add_f32_e32 v2, v87, v2
	v_add_f32_e32 v2, v88, v2
	v_add_f32_e32 v2, v89, v2
	v_cvt_pk_bf16_f32 v158, v84, v85
	v_cvt_pk_bf16_f32 v159, v86, v87
	s_waitcnt lgkmcnt(10)
	v_mfma_f32_32x32x16_bf16 v[112:127], v[160:163], v[140:143], v[48:63]
	ds_read_b64_tr_b16 v[10:11], v14 offset:25600
	ds_read_b64_tr_b16 v[12:13], v14 offset:26112
	v_add_f32_e32 v2, v90, v2
	v_add_f32_e32 v2, v91, v2
	v_add_f32_e32 v2, v92, v2
	v_add_f32_e32 v2, v93, v2
	v_cvt_pk_bf16_f32 v152, v88, v89
	v_cvt_pk_bf16_f32 v153, v90, v91
	s_waitcnt lgkmcnt(11)
	v_mfma_f32_32x32x16_bf16 v[96:111], v[192:195], v[136:139], v[96:111]
	ds_read_b64_tr_b16 v[160:161], v14 offset:29696
	ds_read_b64_tr_b16 v[162:163], v14 offset:30208
	v_add_f32_e32 v2, v94, v2
	v_add_f32_e32 v2, v95, v2
	v_add_f32_e32 v2, v64, v2
	v_add_f32_e32 v2, v65, v2
	v_cvt_pk_bf16_f32 v154, v92, v93
	v_cvt_pk_bf16_f32 v155, v94, v95
	s_waitcnt lgkmcnt(12)
	v_mfma_f32_32x32x16_bf16 v[112:127], v[188:191], v[136:139], v[112:127]
	ds_read_b64_tr_b16 v[196:197], v14 offset:26624
	ds_read_b64_tr_b16 v[198:199], v14 offset:27136
	v_add_f32_e32 v2, v66, v2
	v_add_f32_e32 v2, v67, v2
	v_add_f32_e32 v2, v68, v2
	v_add_f32_e32 v6, v69, v2
	v_cvt_pk_bf16_f32 v148, v64, v65
	v_cvt_pk_bf16_f32 v149, v66, v67
	ds_read_b128 v[64:67], v200 offset:256
	s_waitcnt lgkmcnt(13)
	v_mfma_f32_32x32x16_bf16 v[96:111], v[184:187], v[132:135], v[96:111]
	ds_read_b64_tr_b16 v[2:3], v14 offset:30720
	ds_read_b64_tr_b16 v[4:5], v14 offset:31232
	v_add_f32_e32 v6, v70, v6
	v_add_f32_e32 v6, v71, v6
	v_add_f32_e32 v6, v72, v6
	v_add_f32_e32 v15, v73, v6
	v_cvt_pk_bf16_f32 v150, v68, v69
	v_cvt_pk_bf16_f32 v151, v70, v71
	ds_read_b128 v[68:71], v200 offset:288
	s_waitcnt lgkmcnt(14)
	v_mfma_f32_32x32x16_bf16 v[112:127], v[180:183], v[132:135], v[112:127]
	ds_read_b64_tr_b16 v[6:7], v14 offset:27648
	ds_read_b64_tr_b16 v[8:9], v14 offset:28160
	v_add_f32_e32 v15, v74, v15
	v_add_f32_e32 v15, v75, v15
	v_add_f32_e32 v15, v76, v15
	v_add_f32_e32 v15, v77, v15
	v_cvt_pk_bf16_f32 v144, v72, v73
	v_cvt_pk_bf16_f32 v145, v74, v75
	ds_read_b128 v[72:75], v200 offset:384
	s_waitcnt lgkmcnt(14)
	v_mfma_f32_32x32x16_bf16 v[96:111], v[176:179], v[128:131], v[96:111]
	ds_read_b64_tr_b16 v[192:193], v14 offset:31744
	ds_read_b64_tr_b16 v[194:195], v14 offset:32256
	v_add_f32_e32 v14, v78, v15
	v_add_f32_e32 v14, v79, v14
	v_add_f32_e32 v80, 0, v14
	v_cvt_pk_bf16_f32 v146, v76, v77
	v_cvt_pk_bf16_f32 v147, v78, v79
	v_mfma_f32_32x32x16_bf16 v[112:127], v[172:175], v[128:131], v[112:127]
	s_add_i32 s16, s46, -1
	s_add_i32 s17, s47, 0xfffe8000
	s_lshr_b32 s16, s16, 2
	s_and_b32 s22, s17, 0x18000
	s_mul_i32 s100, s16, 0x180000
	s_lshl_b32 s26, s22, 1
	s_add_u32 s100, s100, s26
	s_add_u32 s100, s100, s98
	s_addc_u32 s101, s99, 0
	s_add_i32 s16, s25, s74
	s_mov_b32 s17, m0
	s_mov_b32 m0, s16
	s_nop 0
	global_load_lds_dwordx4 v236, s[100:101]
	s_mov_b32 m0, s17
	s_add_i32 s50, s46, -3
	s_add_i32 s17, s47, 0xffff8000
	s_lshr_b32 s16, s50, 2
	s_and_b32 s22, s17, 0x18000
	s_mul_i32 s100, s16, 0x180000
	s_lshl_b32 s26, s22, 1
	s_add_u32 s100, s100, s26
	s_add_u32 s100, s100, s98
	s_addc_u32 s101, s99, 0
	s_add_i32 s16, s78, s75
	s_mov_b32 s17, m0
	s_mov_b32 m0, s16
	s_nop 0
	global_load_lds_dwordx4 v237, s[100:101]
	s_mov_b32 m0, s17
	v_add_f32_e32 v241, v0, v80
	s_waitcnt lgkmcnt(2)
	v_add_f32_e32 v82, v98, v66
	v_add_f32_e32 v83, v99, v67
	s_waitcnt lgkmcnt(1)
	v_add_f32_e32 v84, v100, v68
	v_add_f32_e32 v85, v101, v69
	s_waitcnt lgkmcnt(0)
	v_add_f32_e32 v14, v112, v72
	v_add_f32_e32 v15, v113, v73
	v_add_f32_e32 v66, v114, v74
	v_add_f32_e32 v67, v115, v75
	ds_read_b128 v[72:75], v200 offset:416
	v_add_f32_e32 v86, v102, v70
	v_add_f32_e32 v87, v103, v71
	v_add_f32_e32 v64, v96, v64
	v_add_f32_e32 v65, v97, v65
	s_waitcnt lgkmcnt(0)
	v_add_f32_e32 v68, v116, v72
	v_add_f32_e32 v69, v117, v73
	v_add_f32_e32 v70, v118, v74
	v_add_f32_e32 v71, v119, v75
	ds_read_b128 v[72:75], v200 offset:320
	ds_read_b128 v[76:79], v200 offset:448
	v_max_f32_e32 v81, v64, v65
	v_max3_f32 v81, v81, v14, v66
	v_max3_f32 v81, v81, v67, v84
	s_waitcnt lgkmcnt(1)
	v_add_f32_e32 v88, v104, v72
	v_add_f32_e32 v89, v105, v73
	s_waitcnt lgkmcnt(0)
	v_add_f32_e32 v72, v120, v76
	v_add_f32_e32 v73, v121, v77
	v_add_f32_e32 v90, v106, v74
	v_add_f32_e32 v91, v107, v75
	v_add_f32_e32 v74, v122, v78
	v_add_f32_e32 v75, v123, v79
	ds_read_b128 v[76:79], v200 offset:352
	ds_read_b128 v[94:97], v200 offset:480
	v_max3_f32 v81, v81, v85, v68
	v_max3_f32 v81, v81, v69, v88
	v_max3_f32 v81, v81, v89, v72
	s_waitcnt lgkmcnt(1)
	v_add_f32_e32 v92, v108, v76
	v_add_f32_e32 v93, v109, v77
	s_waitcnt lgkmcnt(0)
	v_add_f32_e32 v76, v124, v94
	v_add_f32_e32 v77, v125, v95
	v_add_f32_e32 v94, v110, v78
	v_add_f32_e32 v95, v111, v79
	v_add_f32_e32 v78, v126, v96
	v_add_f32_e32 v79, v127, v97
	v_max3_f32 v96, v82, v83, v15
	v_max3_f32 v96, v96, v86, v87
	v_max3_f32 v96, v96, v70, v71
	v_max3_f32 v96, v96, v90, v91
	v_max3_f32 v96, v96, v74, v75
	v_max3_f32 v81, v81, v73, v92
	v_max3_f32 v96, v96, v94, v95
	v_max3_f32 v81, v81, v93, v76
	v_max3_f32 v96, v96, v78, v79
	v_max3_f32 v0, v81, v77, v96
	v_mov_b32_e32 v80, v0
	s_nop 1
	v_permlane32_swap_b32_e32 v0, v80
	v_max_f32_e32 v80, v80, v80
	v_max_f32_e32 v0, v0, v0
	v_max_f32_e32 v0, v0, v80
	v_cmp_lt_f32_e32 vcc, s36, v0
	s_cmp_lg_u64 vcc, 0
	s_cselect_b64 s[16:17], -1, 0
	s_cbranch_vccnz .LBB0_1327

.LBB0_1331:
	v_mov_b32_e32 v236, 0x6101000
	v_mov_b32_e32 v237, 0x6100000
	s_xor_b64 s[16:17], s[4:5], -1
	s_add_i32 s2, s50, 1
	s_cmp_ge_u32 s2, s77
	s_cbranch_scc1 .LBB0_1381
	s_lshl_b32 s4, s50, 6
	s_addk_i32 s4, 0x7b
	v_add_u32_e32 v0, s4, v221
	s_lshl_b32 s4, s24, 2
	s_sub_i32 s65, 0, s4
	s_lshl_b32 s4, s50, 8
	s_add_i32 s4, s4, 0
	s_add_i32 s4, s4, 0x14800
	v_cmp_gt_u32_e64 s[2:3], 32, v217
	v_subrev_u32_e32 v0, s71, v0
	s_add_i32 s58, s50, 2
	v_lshl_add_u32 v14, v219, 4, s4
	s_lshl_b32 s79, s50, 15
	.p2align	6
